# attention QK cluster: next-tile prefetch (address VALU + loads) packed into the first MFMA gaps so the loads are issued earlier
# baseline (speedup 1.0000x reference)
; #define MFMA32(a, b, c) __builtin_amdgcn_mfma_f32_32x32x16_bf16((a), (b), (c), 0, 0, 0)
; template <int DK, int DV>
; DI void attn_map(f32x16 (&O)[DV / 32], float& lsum, const u16* qrow, const u16* K1, int ldk1, const u16* K2, int ldk2, const u16* Vt, int nkeys, char* smem) {
;     ...
;     __syncthreads();
; #pragma unroll
;     for (int i = 0; i < NKR; ++i) { int id = tid + i * 256; int row = id / KCH, cc = id - row * KCH; *(u32x4*)(Ks + row * KST + cc * 8) = kreg[i]; }
; #pragma unroll
;     for (int i = 0; i < NVR; ++i) {
;       int id = tid + i * 256; int row = id >> 3, cc = id & 7;
;       u16* base = Vs + row * VST + (cc >> 1) * 16 + (cc & 1) * 4;
;       u32x2 t0 = {vreg[i].x, vreg[i].y}, t1 = {vreg[i].z, vreg[i].w};
;       *(u32x2*)base = t0; *(u32x2*)(base + 8) = t1;
;     }
;     __syncthreads();
;     if (k0 + 64 < nkeys) ATT_LOAD(k0 + 64)
;     f32x16 s[2];
;     __builtin_amdgcn_s_setprio(1);
; #pragma unroll
;     for (int j = 0; j < 2; ++j) {
; #pragma unroll
;       for (int ks = 0; ks < DK / 16; ++ks) {
;         bf16x8 kf = *(const bf16x8*)(Ks + (j * 32 + r) * KST + ks * 16 + 8 * h);
;         s[j] = (ks == 0) ? MFMA32(kf, qf[ks], negm) : MFMA32(kf, qf[ks], s[j]);
;       }
;     }
;     {
;       constexpr int NQK = 2 * (DK / 16);
;       __builtin_amdgcn_sched_group_barrier(0x100, 2, 0);
; #pragma unroll
;       for (int q = 0; q < NQK - 2; ++q) { __builtin_amdgcn_sched_group_barrier(0x008, 1, 0); __builtin_amdgcn_sched_group_barrier(0x100, 1, 0); }
;       __builtin_amdgcn_sched_group_barrier(0x008, 2, 0);
;     }
.LBB0_382:
	s_cmpk_gt_u32 s10, 0x10bf
	s_cselect_b64 s[8:9], -1, 0
	s_and_b64 vcc, exec, s[8:9]
	s_barrier
	s_waitcnt vmcnt(5)
	ds_write_b128 v188, v[144:147]
	s_waitcnt vmcnt(4)
	ds_write_b128 v189, v[148:151]
	s_waitcnt vmcnt(3)
	ds_write2_b64 v190, v[152:153], v[154:155] offset0:128 offset1:130
	s_waitcnt vmcnt(2)
	ds_write2_b64 v191, v[156:157], v[158:159] offset0:128 offset1:130
	s_waitcnt vmcnt(1)
	ds_write2_b64 v192, v[160:161], v[162:163] offset0:128 offset1:130
	s_waitcnt vmcnt(0)
	ds_write2_b64 v193, v[164:165], v[166:167] offset0:128 offset1:130
	s_waitcnt lgkmcnt(0)
	s_barrier
	s_cbranch_vccnz .Lqk_last_A
	s_setprio 1
	ds_read_b128 v[200:203], v168
	ds_read_b128 v[204:207], v168 offset:32
	ds_read_b128 v[208:211], v168 offset:64
	ds_read_b128 v[212:215], v168 offset:96
	s_waitcnt lgkmcnt(3)
	v_mfma_f32_32x32x16_bf16 v[96:111], v[200:203], v[128:131], v[16:31]
	ds_read_b128 v[216:219], v168 offset:4608
	ds_read_b128 v[200:203], v168 offset:9216
	v_lshl_add_u64 v[236:237], v[186:187], 0, s[6:7]
	global_load_dwordx4 v[144:147], v[236:237], off
	v_lshl_add_u64 v[236:237], v[184:185], 0, s[6:7]
	global_load_dwordx4 v[148:151], v[236:237], off
	s_waitcnt lgkmcnt(4)
	v_mfma_f32_32x32x16_bf16 v[96:111], v[204:207], v[132:135], v[96:111]
	ds_read_b128 v[220:223], v168 offset:4640
	ds_read_b128 v[204:207], v168 offset:13824
	v_lshl_add_u64 v[236:237], v[182:183], 0, s[6:7]
	global_load_dwordx4 v[152:155], v[236:237], off
	v_lshl_add_u64 v[236:237], v[180:181], 0, s[6:7]
	global_load_dwordx4 v[156:159], v[236:237], off
	s_waitcnt lgkmcnt(5)
	v_mfma_f32_32x32x16_bf16 v[96:111], v[208:211], v[136:139], v[96:111]
	ds_read_b128 v[224:227], v168 offset:4672
	ds_read_b128 v[208:211], v168 offset:18432
	v_lshl_add_u64 v[236:237], v[178:179], 0, s[6:7]
	global_load_dwordx4 v[160:163], v[236:237], off
	v_lshl_add_u64 v[236:237], v[176:177], 0, s[6:7]
	global_load_dwordx4 v[164:167], v[236:237], off
	s_waitcnt lgkmcnt(6)
	v_mfma_f32_32x32x16_bf16 v[96:111], v[212:215], v[140:143], v[96:111]
	ds_read_b128 v[228:231], v168 offset:4704
	ds_read_b128 v[212:215], v168 offset:23040
	s_waitcnt lgkmcnt(7)
	v_mfma_f32_32x32x16_bf16 v[112:127], v[216:219], v[128:131], v[16:31]
	ds_read_b128 v[216:219], v168 offset:9248
	s_waitcnt lgkmcnt(6)
	v_mfma_f32_32x32x16_bf16 v[112:127], v[220:223], v[132:135], v[112:127]
	ds_read_b128 v[220:223], v168 offset:13856
	s_waitcnt lgkmcnt(5)
	v_mfma_f32_32x32x16_bf16 v[112:127], v[224:227], v[136:139], v[112:127]
	ds_read_b128 v[224:227], v168 offset:18464
	s_waitcnt lgkmcnt(4)
	v_mfma_f32_32x32x16_bf16 v[112:127], v[228:231], v[140:143], v[112:127]
	ds_read_b128 v[228:231], v168 offset:23072
	s_setprio 0

; #define MFMA32(a, b, c) __builtin_amdgcn_mfma_f32_32x32x16_bf16((a), (b), (c), 0, 0, 0)
; template <int DK, int DV>
; DI void attn_map(f32x16 (&O)[DV / 32], float& lsum, const u16* qrow, const u16* K1, int ldk1, const u16* K2, int ldk2, const u16* Vt, int nkeys, char* smem) {
;     ...
;     __syncthreads();
; #pragma unroll
;     for (int i = 0; i < NKR; ++i) { int id = tid + i * 256; int row = id / KCH, cc = id - row * KCH; *(u32x4*)(Ks + row * KST + cc * 8) = kreg[i]; }
; #pragma unroll
;     for (int i = 0; i < NVR; ++i) {
;       int id = tid + i * 256; int row = id >> 3, cc = id & 7;
;       u16* base = Vs + row * VST + (cc >> 1) * 16 + (cc & 1) * 4;
;       u32x2 t0 = {vreg[i].x, vreg[i].y}, t1 = {vreg[i].z, vreg[i].w};
;       *(u32x2*)base = t0; *(u32x2*)(base + 8) = t1;
;     }
;     __syncthreads();
;     if (k0 + 64 < nkeys) ATT_LOAD(k0 + 64)
;     f32x16 s[2];
;     __builtin_amdgcn_s_setprio(1);
; #pragma unroll
;     for (int j = 0; j < 2; ++j) {
; #pragma unroll
;       for (int ks = 0; ks < DK / 16; ++ks) {
;         bf16x8 kf = *(const bf16x8*)(Ks + (j * 32 + r) * KST + ks * 16 + 8 * h);
;         s[j] = (ks == 0) ? MFMA32(kf, qf[ks], negm) : MFMA32(kf, qf[ks], s[j]);
;       }
;     }
;     {
;       constexpr int NQK = 2 * (DK / 16);
;       __builtin_amdgcn_sched_group_barrier(0x100, 2, 0);
; #pragma unroll
;       for (int q = 0; q < NQK - 2; ++q) { __builtin_amdgcn_sched_group_barrier(0x008, 1, 0); __builtin_amdgcn_sched_group_barrier(0x100, 1, 0); }
;       __builtin_amdgcn_sched_group_barrier(0x008, 2, 0);
;     }
.LBB0_404:
	s_cmpk_gt_u32 s10, 0x10bf
	s_cselect_b64 s[6:7], -1, 0
	s_and_b64 vcc, exec, s[6:7]
	s_barrier
	s_waitcnt vmcnt(5)
	ds_write_b128 v189, v[144:147]
	s_waitcnt vmcnt(4)
	ds_write_b128 v190, v[148:151]
	s_waitcnt vmcnt(3)
	ds_write2_b64 v191, v[152:153], v[154:155] offset0:128 offset1:130
	s_waitcnt vmcnt(2)
	ds_write2_b64 v192, v[156:157], v[158:159] offset0:128 offset1:130
	s_waitcnt vmcnt(1)
	ds_write2_b64 v193, v[160:161], v[162:163] offset0:128 offset1:130
	s_waitcnt vmcnt(0)
	ds_write2_b64 v194, v[164:165], v[166:167] offset0:128 offset1:130
	s_waitcnt lgkmcnt(0)
	s_barrier
	s_cbranch_vccnz .Lqk_last_B
	s_setprio 1
	ds_read_b128 v[200:203], v195
	ds_read_b128 v[204:207], v195 offset:32
	ds_read_b128 v[208:211], v195 offset:64
	ds_read_b128 v[212:215], v195 offset:96
	s_waitcnt lgkmcnt(3)
	v_mfma_f32_32x32x16_bf16 v[96:111], v[200:203], v[128:131], v[80:95]
	ds_read_b128 v[216:219], v195 offset:4608
	ds_read_b128 v[200:203], v195 offset:9216
	v_lshl_add_u64 v[236:237], v[182:183], 0, v[168:169]
	global_load_dwordx4 v[144:147], v[186:187], off
	global_load_dwordx4 v[148:151], v[184:185], off
	global_load_dwordx4 v[152:155], v[236:237], off
	s_waitcnt lgkmcnt(4)
	v_mfma_f32_32x32x16_bf16 v[96:111], v[204:207], v[132:135], v[96:111]
	ds_read_b128 v[220:223], v195 offset:4640
	ds_read_b128 v[204:207], v195 offset:13824
	v_lshl_add_u64 v[236:237], v[180:181], 0, v[168:169]
	global_load_dwordx4 v[156:159], v[236:237], off
	v_lshl_add_u64 v[236:237], v[178:179], 0, v[168:169]
	global_load_dwordx4 v[160:163], v[236:237], off
	s_waitcnt lgkmcnt(5)
	v_mfma_f32_32x32x16_bf16 v[96:111], v[208:211], v[136:139], v[96:111]
	ds_read_b128 v[224:227], v195 offset:4672
	ds_read_b128 v[208:211], v195 offset:18432
	v_lshl_add_u64 v[236:237], v[176:177], 0, v[168:169]
	global_load_dwordx4 v[164:167], v[236:237], off
	s_waitcnt lgkmcnt(6)
	v_mfma_f32_32x32x16_bf16 v[96:111], v[212:215], v[140:143], v[96:111]
	ds_read_b128 v[228:231], v195 offset:4704
	ds_read_b128 v[212:215], v195 offset:23040
	s_waitcnt lgkmcnt(7)
	v_mfma_f32_32x32x16_bf16 v[112:127], v[216:219], v[128:131], v[80:95]
	ds_read_b128 v[216:219], v195 offset:9248
	s_waitcnt lgkmcnt(6)
	v_mfma_f32_32x32x16_bf16 v[112:127], v[220:223], v[132:135], v[112:127]
	ds_read_b128 v[220:223], v195 offset:13856
	s_waitcnt lgkmcnt(5)
	v_mfma_f32_32x32x16_bf16 v[112:127], v[224:227], v[136:139], v[112:127]
	ds_read_b128 v[224:227], v195 offset:18464
	s_waitcnt lgkmcnt(4)
	v_mfma_f32_32x32x16_bf16 v[112:127], v[228:231], v[140:143], v[112:127]
	ds_read_b128 v[228:231], v195 offset:23072
	s_setprio 0

; #define MFMA32(a, b, c) __builtin_amdgcn_mfma_f32_32x32x16_bf16((a), (b), (c), 0, 0, 0)
; template <int DK, int DV>
; DI void attn_map(f32x16 (&O)[DV / 32], float& lsum, const u16* qrow, const u16* K1, int ldk1, const u16* K2, int ldk2, const u16* Vt, int nkeys, char* smem) {
;     ...
;     __syncthreads();
; #pragma unroll
;     for (int i = 0; i < NKR; ++i) { int id = tid + i * 256; int row = id / KCH, cc = id - row * KCH; *(u32x4*)(Ks + row * KST + cc * 8) = kreg[i]; }
; #pragma unroll
;     for (int i = 0; i < NVR; ++i) {
;       int id = tid + i * 256; int row = id >> 3, cc = id & 7;
;       u16* base = Vs + row * VST + (cc >> 1) * 16 + (cc & 1) * 4;
;       u32x2 t0 = {vreg[i].x, vreg[i].y}, t1 = {vreg[i].z, vreg[i].w};
;       *(u32x2*)base = t0; *(u32x2*)(base + 8) = t1;
;     }
;     __syncthreads();
;     if (k0 + 64 < nkeys) ATT_LOAD(k0 + 64)
;     f32x16 s[2];
;     __builtin_amdgcn_s_setprio(1);
; #pragma unroll
;     for (int j = 0; j < 2; ++j) {
; #pragma unroll
;       for (int ks = 0; ks < DK / 16; ++ks) {
;         bf16x8 kf = *(const bf16x8*)(Ks + (j * 32 + r) * KST + ks * 16 + 8 * h);
;         s[j] = (ks == 0) ? MFMA32(kf, qf[ks], negm) : MFMA32(kf, qf[ks], s[j]);
;       }
;     }
;     {
;       constexpr int NQK = 2 * (DK / 16);
;       __builtin_amdgcn_sched_group_barrier(0x100, 2, 0);
; #pragma unroll
;       for (int q = 0; q < NQK - 2; ++q) { __builtin_amdgcn_sched_group_barrier(0x008, 1, 0); __builtin_amdgcn_sched_group_barrier(0x100, 1, 0); }
;       __builtin_amdgcn_sched_group_barrier(0x008, 2, 0);
;     }
.LBB0_436:
	s_add_u32 s6, s10, 64
	s_addc_u32 s7, s11, 0
	s_cmpk_gt_u32 s6, 0x10bf
	s_cselect_b64 s[8:9], -1, 0
	s_and_b64 vcc, exec, s[8:9]
	s_barrier
	s_waitcnt vmcnt(4)
	ds_write_b128 v149, v[120:123]
	s_waitcnt vmcnt(3)
	ds_write_b128 v164, v[124:127]
	s_waitcnt vmcnt(2)
	ds_write_b128 v165, v[128:131]
	s_waitcnt vmcnt(1)
	ds_write2_b64 v166, v[132:133], v[134:135] offset0:128 offset1:130
	s_waitcnt vmcnt(0)
	ds_write2_b64 v167, v[136:137], v[138:139] offset0:128 offset1:130
	s_waitcnt lgkmcnt(0)
	s_barrier
	s_cbranch_vccnz .Lqk_last_C
	s_setprio 1
	ds_read_b128 v[190:193], v143
	ds_read_b128 v[194:197], v143 offset:32
	ds_read_b128 v[198:201], v143 offset:64
	ds_read_b128 v[202:205], v143 offset:96
	s_waitcnt lgkmcnt(3)
	v_mfma_f32_32x32x16_bf16 v[64:79], v[190:193], v[96:99], v[16:31]
	ds_read_b128 v[206:209], v143 offset:128
	ds_read_b128 v[190:193], v168 offset:13312
	v_lshl_add_u64 v[188:189], v[162:163], 0, s[10:11]
	v_lshlrev_b64 v[188:189], v144, v[188:189]
	v_lshl_add_u64 v[188:189], v[146:147], 0, v[188:189]
	global_load_dwordx4 v[120:123], v[188:189], off
	s_waitcnt lgkmcnt(4)
	v_mfma_f32_32x32x16_bf16 v[64:79], v[194:197], v[100:103], v[64:79]
	ds_read_b128 v[210:213], v143 offset:160
	ds_read_b128 v[194:197], v168 offset:17920
	v_lshl_add_u64 v[188:189], v[160:161], 0, s[10:11]
	v_lshlrev_b64 v[188:189], v148, v[188:189]
	v_lshl_add_u64 v[188:189], v[150:151], 0, v[188:189]
	global_load_dwordx4 v[124:127], v[188:189], off
	s_waitcnt lgkmcnt(5)
	v_mfma_f32_32x32x16_bf16 v[64:79], v[198:201], v[104:107], v[64:79]
	ds_read_b128 v[214:217], v143 offset:6656
	ds_read_b128 v[198:201], v168 offset:13344
	v_lshl_add_u64 v[188:189], v[158:159], 0, s[10:11]
	v_lshlrev_b64 v[188:189], v142, v[188:189]
	v_lshl_add_u64 v[188:189], v[152:153], 0, v[188:189]
	global_load_dwordx4 v[128:131], v[188:189], off
	s_waitcnt lgkmcnt(6)
	v_mfma_f32_32x32x16_bf16 v[64:79], v[202:205], v[108:111], v[64:79]
	ds_read_b128 v[218:221], v143 offset:6688
	ds_read_b128 v[202:205], v168 offset:17952
	global_load_dwordx4 v[132:135], v[156:157], off
	global_load_dwordx4 v[136:139], v[154:155], off
	s_waitcnt lgkmcnt(7)
	v_mfma_f32_32x32x16_bf16 v[64:79], v[206:209], v[112:115], v[64:79]
	ds_read_b128 v[222:225], v143 offset:6720
	ds_read_b128 v[206:209], v168 offset:13376
	s_waitcnt lgkmcnt(7)
	v_mfma_f32_32x32x16_bf16 v[64:79], v[210:213], v[116:119], v[64:79]
	ds_read_b128 v[226:229], v143 offset:6752
	ds_read_b128 v[210:213], v168 offset:17984
	s_waitcnt lgkmcnt(7)
	v_mfma_f32_32x32x16_bf16 v[80:95], v[214:217], v[96:99], v[16:31]
	ds_read_b128 v[230:233], v143 offset:6784
	ds_read_b128 v[214:217], v168 offset:13408
	s_waitcnt lgkmcnt(7)
	v_mfma_f32_32x32x16_bf16 v[80:95], v[218:221], v[100:103], v[80:95]
	ds_read_b128 v[234:237], v143 offset:6816
	ds_read_b128 v[218:221], v168 offset:18016
	s_waitcnt lgkmcnt(7)
	v_mfma_f32_32x32x16_bf16 v[80:95], v[222:225], v[104:107], v[80:95]
	s_waitcnt lgkmcnt(5)
	v_mfma_f32_32x32x16_bf16 v[80:95], v[226:229], v[108:111], v[80:95]
	s_waitcnt lgkmcnt(3)
	v_mfma_f32_32x32x16_bf16 v[80:95], v[230:233], v[112:115], v[80:95]
	s_waitcnt lgkmcnt(1)
	v_mfma_f32_32x32x16_bf16 v[80:95], v[234:237], v[116:119], v[80:95]
	s_setprio 0

; #define MFMA32(a, b, c) __builtin_amdgcn_mfma_f32_32x32x16_bf16((a), (b), (c), 0, 0, 0)
; template <int DK, int DV>
; DI void attn_map(f32x16 (&O)[DV / 32], float& lsum, const u16* qrow, const u16* K1, int ldk1, const u16* K2, int ldk2, const u16* Vt, int nkeys, char* smem) {
;     ...
;     __syncthreads();
; #pragma unroll
;     for (int i = 0; i < NKR; ++i) { int id = tid + i * 256; int row = id / KCH, cc = id - row * KCH; *(u32x4*)(Ks + row * KST + cc * 8) = kreg[i]; }
; #pragma unroll
;     for (int i = 0; i < NVR; ++i) {
;       int id = tid + i * 256; int row = id >> 3, cc = id & 7;
;       u16* base = Vs + row * VST + (cc >> 1) * 16 + (cc & 1) * 4;
;       u32x2 t0 = {vreg[i].x, vreg[i].y}, t1 = {vreg[i].z, vreg[i].w};
;       *(u32x2*)base = t0; *(u32x2*)(base + 8) = t1;
;     }
;     __syncthreads();
;     if (k0 + 64 < nkeys) ATT_LOAD(k0 + 64)
;     f32x16 s[2];
;     __builtin_amdgcn_s_setprio(1);
; #pragma unroll
;     for (int j = 0; j < 2; ++j) {
; #pragma unroll
;       for (int ks = 0; ks < DK / 16; ++ks) {
;         bf16x8 kf = *(const bf16x8*)(Ks + (j * 32 + r) * KST + ks * 16 + 8 * h);
;         s[j] = (ks == 0) ? MFMA32(kf, qf[ks], negm) : MFMA32(kf, qf[ks], s[j]);
;       }
;     }
;     {
;       constexpr int NQK = 2 * (DK / 16);
;       __builtin_amdgcn_sched_group_barrier(0x100, 2, 0);
; #pragma unroll
;       for (int q = 0; q < NQK - 2; ++q) { __builtin_amdgcn_sched_group_barrier(0x008, 1, 0); __builtin_amdgcn_sched_group_barrier(0x100, 1, 0); }
;       __builtin_amdgcn_sched_group_barrier(0x008, 2, 0);
;     }
.LBB0_447:
	s_cmpk_gt_u32 s12, 0x10bf
	s_cselect_b64 s[8:9], -1, 0
	s_and_b64 vcc, exec, s[8:9]
	s_barrier
	s_waitcnt vmcnt(3)
	ds_write_b128 v139, v[112:115]
	s_waitcnt vmcnt(1)
	ds_write_b128 v140, v[116:119]
	ds_write2_b64 v141, v[120:121], v[122:123] offset0:128 offset1:130
	s_waitcnt vmcnt(0)
	ds_write2_b64 v142, v[124:125], v[126:127] offset0:128 offset1:130
	s_waitcnt lgkmcnt(0)
	s_barrier
	s_cbranch_vccnz .Lqk_last_D
	s_setprio 1
	ds_read_b128 v[200:203], v143
	ds_read_b128 v[204:207], v143 offset:32
	ds_read_b128 v[208:211], v143 offset:64
	ds_read_b128 v[212:215], v143 offset:96
	s_waitcnt lgkmcnt(3)
	v_mfma_f32_32x32x16_bf16 v[64:79], v[200:203], v[96:99], v[16:31]
	ds_read_b128 v[216:219], v143 offset:4608
	ds_read_b128 v[200:203], v143 offset:9216
	v_lshl_add_u64 v[236:237], v[136:137], 0, s[6:7]
	global_load_dwordx4 v[112:115], v[236:237], off
	v_lshl_add_u64 v[236:237], v[134:135], 0, s[6:7]
	global_load_dwordx4 v[116:119], v[236:237], off
	s_waitcnt lgkmcnt(4)
	v_mfma_f32_32x32x16_bf16 v[64:79], v[204:207], v[100:103], v[64:79]
	ds_read_b128 v[220:223], v143 offset:4640
	ds_read_b128 v[204:207], v143 offset:13824
	v_lshl_add_u64 v[236:237], v[132:133], 0, s[6:7]
	global_load_dwordx4 v[120:123], v[236:237], off
	v_lshl_add_u64 v[236:237], v[130:131], 0, s[6:7]
	global_load_dwordx4 v[124:127], v[236:237], off
	s_waitcnt lgkmcnt(5)
	v_mfma_f32_32x32x16_bf16 v[64:79], v[208:211], v[104:107], v[64:79]
	ds_read_b128 v[224:227], v143 offset:4672
	ds_read_b128 v[208:211], v143 offset:9248
	s_waitcnt lgkmcnt(6)
	v_mfma_f32_32x32x16_bf16 v[64:79], v[212:215], v[108:111], v[64:79]
	ds_read_b128 v[228:231], v143 offset:4704
	ds_read_b128 v[212:215], v143 offset:13856
	s_waitcnt lgkmcnt(7)
	v_mfma_f32_32x32x16_bf16 v[80:95], v[216:219], v[96:99], v[16:31]
	ds_read_b128 v[216:219], v143 offset:9280
	s_waitcnt lgkmcnt(6)
	v_mfma_f32_32x32x16_bf16 v[80:95], v[220:223], v[100:103], v[80:95]
	ds_read_b128 v[220:223], v143 offset:13888
	s_waitcnt lgkmcnt(5)
	v_mfma_f32_32x32x16_bf16 v[80:95], v[224:227], v[104:107], v[80:95]
	ds_read_b128 v[224:227], v143 offset:9312
	s_waitcnt lgkmcnt(4)
	v_mfma_f32_32x32x16_bf16 v[80:95], v[228:231], v[108:111], v[80:95]
	ds_read_b128 v[228:231], v143 offset:13920
	s_setprio 0
